# LayerNorm phases, context rows: the row's split-K partial tiles are requested together at the top of the iteration (prefetch loads into an unread register) instead of one dependent memory round trip p
# speedup vs baseline: 1.0513x; 1.0009x over previous
; template <int PR>
; DI void prep_rows(const int lane, const Params& p, int l, int which, int rbeg, int rend, int gw, int nw) {
;     ...
;                 const bf16_t* src = P_WSB(OFF_Z) + (size_t)r2 * 1024;
; #pragma unroll
;                 for (int i = 0; i < 4; i += 2) { const u32x4 zz = *(const u32x4*)(src + PCOL(i)); const u32x2 zl = {zz[0], zz[1]}, zh = {zz[2], zz[3]}; v[rr][i] = unpk4(zl); v[rr][i + 1] = unpk4(zh); }
;             }
;         }
;         if (row >= TL && !raw) {
;             const bool rawres = (which == 1 && l == 0);
;             const int lp = which ? l : l - 1;
;             const float* gp = P_WSF(OFF_MOD) + (size_t)(lp * 9 + 8) * 6144 + (which ? 2048 : 5120);
;             if (rawres) {
; #pragma unroll
;                 for (int rr = 0; rr < PR; ++rr) {
;                     const float* cs = P_IN(2) + (size_t)(row + rr - TL) * 1024;
; #pragma unroll
;                     for (int i = 0; i < 4; ++i) v[rr][i] = *(const f32x4*)(cs + PCOL(i));
;                 }
;             } else {
;                 const int lj = which ? (l * 2 - 1) : (l * 2 - 2);
;                 const float* lg2 = P_IN(6) + lj * 1024; const float* lb2 = P_IN(7) + lj * 1024;
; #pragma unroll
;                 for (int i = 0; i < 4; ++i) {
;                     const f32x4 g = *(const f32x4*)(lg2 + PCOL(i)), b = *(const f32x4*)(lb2 + PCOL(i));
; #pragma unroll
;                     for (int rr = 0; rr < PR; ++rr) { const f32x2 st = *(const f32x2*)(P_WSF(OFF_STATS) + 2 * (row + rr)); v[rr][i] = (v[rr][i] - st[0]) * st[1] * g + b; }
;                 }
;             }
; #pragma unroll
;             for (int i = 0; i < 4; ++i) {
;                 const int c = PCOL(i);
;                 const f32x4 gv = *(const f32x4*)(gp + c);
; #pragma unroll
;                 for (int rr = 0; rr < PR; ++rr) {
;                     const bf16_t* pp = P_WSB(OFF_PART) + (size_t)(row + rr - TL) * 1024 + c;
;                     f32x4 a = unpk4(*(const u32x2*)pp);
; #pragma unroll
;                     for (int k = 1; k < NSPLIT_WO; ++k) a += unpk4(*(const u32x2*)(pp + (size_t)k * TC * 1024));
.LBB0_179:
	v_add_co_u32_e32 v0, vcc, 0xf86c0000, v52
	s_mov_b32 s3, 0xf86c1000
	s_nop 0
	v_addc_co_u32_e32 v1, vcc, -1, v53, vcc
	v_add_co_u32_e32 v4, vcc, s3, v52
	global_load_dwordx4 v[0:3], v[0:1], off
	s_nop 0
	v_addc_co_u32_e32 v5, vcc, -1, v53, vcc
	global_load_dwordx4 v[6:9], v[4:5], off offset:-3072
	v_mov_b32_e32 v236, v168
	v_mov_b32_e32 v237, 0
	v_lshlrev_b64 v[236:237], 11, v[236:237]
	v_lshl_add_u64 v[236:237], v[46:47], 0, v[236:237]
	v_mov_b32_e32 v235, 0
	global_load_dwordx4 v[228:231], v[236:237], off
	global_load_dwordx4 v[228:231], v[236:237], off offset:1024
	v_mov_b32_e32 v234, 0x400000
	v_lshl_add_u64 v[238:239], v[236:237], 0, v[234:235]
	global_load_dwordx4 v[228:231], v[238:239], off
	global_load_dwordx4 v[228:231], v[238:239], off offset:1024
	v_mov_b32_e32 v234, 0x800000
	v_lshl_add_u64 v[238:239], v[236:237], 0, v[234:235]
	global_load_dwordx4 v[228:231], v[238:239], off
	global_load_dwordx4 v[228:231], v[238:239], off offset:1024
	v_mov_b32_e32 v234, 0xc00000
	v_lshl_add_u64 v[238:239], v[236:237], 0, v[234:235]
	global_load_dwordx4 v[228:231], v[238:239], off
	global_load_dwordx4 v[228:231], v[238:239], off offset:1024
	v_add_u32_e32 v58, 0x4000, v168
	s_movk_i32 s3, 0x3fff
	v_cmp_lt_i32_e32 vcc, s3, v58
	s_waitcnt vmcnt(0)
	v_lshlrev_b32_e32 v60, 16, v0
	v_and_b32_e32 v61, 0xffff0000, v0
	v_lshlrev_b32_e32 v62, 16, v1
	v_and_b32_e32 v63, 0xffff0000, v1
	v_lshlrev_b32_e32 v64, 16, v2
	v_and_b32_e32 v65, 0xffff0000, v2
	v_lshlrev_b32_e32 v66, 16, v3
	v_and_b32_e32 v67, 0xffff0000, v3
	v_lshlrev_b32_e32 v4, 16, v6
	v_and_b32_e32 v5, 0xffff0000, v6
	v_lshlrev_b32_e32 v6, 16, v7
	v_and_b32_e32 v7, 0xffff0000, v7
	v_lshlrev_b32_e32 v0, 16, v8
	v_and_b32_e32 v1, 0xffff0000, v8
	v_lshlrev_b32_e32 v2, 16, v9
	v_and_b32_e32 v3, 0xffff0000, v9
	s_and_saveexec_b64 s[10:11], vcc
	s_cbranch_execz .LBB0_185
	s_and_b64 vcc, exec, s[6:7]
	s_cbranch_vccz .LBB0_182
	v_readlane_b32 s12, v254, 29
	v_mov_b32_e32 v51, v169
	v_readlane_b32 s13, v254, 30
	s_nop 1
	v_lshl_add_u64 v[8:9], v[50:51], 2, s[12:13]
	global_load_dwordx2 v[68:69], v[8:9], off
	s_nop 0
	global_load_dwordx4 v[8:11], v[34:35], off offset:16
	global_load_dwordx4 v[12:15], v[34:35], off
	global_load_dwordx4 v[16:19], v[36:37], off offset:16
	global_load_dwordx4 v[20:23], v[36:37], off
	s_waitcnt vmcnt(0)
	v_sub_f32_e32 v25, v63, v68
	v_sub_f32_e32 v24, v62, v68
	v_sub_f32_e32 v27, v61, v68
	v_sub_f32_e32 v26, v60, v68
	v_pk_mul_f32 v[26:27], v[68:69], v[26:27] op_sel:[1,0]
	v_pk_mul_f32 v[24:25], v[68:69], v[24:25] op_sel:[1,0]
	v_pk_fma_f32 v[12:13], v[12:13], v[26:27], v[20:21]
	v_pk_fma_f32 v[14:15], v[14:15], v[24:25], v[22:23]
	v_sub_f32_e32 v21, v67, v68
	v_sub_f32_e32 v20, v66, v68
	v_sub_f32_e32 v23, v65, v68
	v_sub_f32_e32 v22, v64, v68
	v_pk_mul_f32 v[22:23], v[68:69], v[22:23] op_sel:[1,0]
	v_pk_mul_f32 v[20:21], v[68:69], v[20:21] op_sel:[1,0]
	v_pk_fma_f32 v[8:9], v[8:9], v[22:23], v[16:17]
	v_pk_fma_f32 v[10:11], v[10:11], v[20:21], v[18:19]
	global_load_dwordx4 v[16:19], v[34:35], off offset:2064
	global_load_dwordx4 v[20:23], v[34:35], off offset:2048
	global_load_dwordx4 v[24:27], v[36:37], off offset:2064
	global_load_dwordx4 v[60:63], v[36:37], off offset:2048
	v_sub_f32_e32 v7, v7, v68
	v_sub_f32_e32 v6, v6, v68
	v_sub_f32_e32 v5, v5, v68
	v_sub_f32_e32 v4, v4, v68
	v_sub_f32_e32 v3, v3, v68
	v_sub_f32_e32 v2, v2, v68
	v_sub_f32_e32 v1, v1, v68
	v_sub_f32_e32 v0, v0, v68
	v_pk_mul_f32 v[4:5], v[68:69], v[4:5] op_sel:[1,0]
	v_pk_mul_f32 v[6:7], v[68:69], v[6:7] op_sel:[1,0]
	v_pk_mul_f32 v[0:1], v[68:69], v[0:1] op_sel:[1,0]
	v_pk_mul_f32 v[2:3], v[68:69], v[2:3] op_sel:[1,0]
	s_waitcnt vmcnt(0)
	v_pk_fma_f32 v[0:1], v[0:1], v[16:17], v[24:25]
	v_pk_fma_f32 v[6:7], v[6:7], v[22:23], v[62:63]
	v_pk_fma_f32 v[4:5], v[4:5], v[20:21], v[60:61]
	v_pk_fma_f32 v[2:3], v[2:3], v[18:19], v[26:27]
	s_cbranch_execz .LBB0_183
	s_branch .LBB0_184

; template <int PR>
; DI void prep_rows(const int lane, const Params& p, int l, int which, int rbeg, int rend, int gw, int nw) {
;     ...
;                 const bf16_t* src = P_WSB(OFF_Z) + (size_t)r2 * 1024;
; #pragma unroll
;                 for (int i = 0; i < 4; i += 2) { const u32x4 zz = *(const u32x4*)(src + PCOL(i)); const u32x2 zl = {zz[0], zz[1]}, zh = {zz[2], zz[3]}; v[rr][i] = unpk4(zl); v[rr][i + 1] = unpk4(zh); }
;     ...
;                     const bf16_t* pp = P_WSB(OFF_PART) + (size_t)(row + rr - TL) * 1024 + c;
;                     f32x4 a = unpk4(*(const u32x2*)pp);
; #pragma unroll
;                     for (int k = 1; k < NSPLIT_WO; ++k) a += unpk4(*(const u32x2*)(pp + (size_t)k * TC * 1024));
;                     if (which == 0) {
; #pragma unroll
;                         for (int k = NSPLIT_WO; k < NSPLIT_M2; ++k) a += unpk4(*(const u32x2*)(pp + (size_t)k * TC * 1024));
.LBB0_507:
	v_add_u32_e32 v80, 0x4000, v78
	s_movk_i32 s2, 0x4000
	v_cndmask_b32_e64 v0, 0, 1, s[10:11]
	v_cmp_gt_i32_e64 s[4:5], s2, v80
	v_cmp_ne_u32_e64 s[2:3], 1, v0
	s_andn2_b64 vcc, exec, s[10:11]
	s_mov_b64 s[52:53], -1
	s_cbranch_vccnz .LBB0_511
	v_add_co_u32_e32 v0, vcc, 0xf86c0000, v74
	s_mov_b32 s16, 0xf86c1000
	s_nop 0
	v_addc_co_u32_e32 v1, vcc, -1, v75, vcc
	global_load_dwordx4 v[4:7], v[0:1], off
	v_add_co_u32_e32 v0, vcc, s16, v74
	s_nop 1
	v_addc_co_u32_e32 v1, vcc, -1, v75, vcc
	global_load_dwordx4 v[8:11], v[0:1], off offset:-3072
	v_mov_b32_e32 v236, v78
	v_mov_b32_e32 v237, 0
	v_lshlrev_b64 v[236:237], 11, v[236:237]
	v_lshl_add_u64 v[236:237], v[66:67], 0, v[236:237]
	v_mov_b32_e32 v235, 0
	global_load_dwordx4 v[228:231], v[236:237], off
	global_load_dwordx4 v[228:231], v[236:237], off offset:1024
	v_mov_b32_e32 v234, 0x400000
	v_lshl_add_u64 v[238:239], v[236:237], 0, v[234:235]
	global_load_dwordx4 v[228:231], v[238:239], off
	global_load_dwordx4 v[228:231], v[238:239], off offset:1024
	v_mov_b32_e32 v234, 0x800000
	v_lshl_add_u64 v[238:239], v[236:237], 0, v[234:235]
	global_load_dwordx4 v[228:231], v[238:239], off
	global_load_dwordx4 v[228:231], v[238:239], off offset:1024
	v_mov_b32_e32 v234, 0xc00000
	v_lshl_add_u64 v[238:239], v[236:237], 0, v[234:235]
	global_load_dwordx4 v[228:231], v[238:239], off
	global_load_dwordx4 v[228:231], v[238:239], off offset:1024
	v_mov_b32_e32 v234, 0x1000000
	v_lshl_add_u64 v[238:239], v[236:237], 0, v[234:235]
	global_load_dwordx4 v[228:231], v[238:239], off
	global_load_dwordx4 v[228:231], v[238:239], off offset:1024
	v_mov_b32_e32 v234, 0x1400000
	v_lshl_add_u64 v[238:239], v[236:237], 0, v[234:235]
	global_load_dwordx4 v[228:231], v[238:239], off
	global_load_dwordx4 v[228:231], v[238:239], off offset:1024
	v_mov_b32_e32 v234, 0x1800000
	v_lshl_add_u64 v[238:239], v[236:237], 0, v[234:235]
	global_load_dwordx4 v[228:231], v[238:239], off
	global_load_dwordx4 v[228:231], v[238:239], off offset:1024
	v_mov_b32_e32 v234, 0x1c00000
	v_lshl_add_u64 v[238:239], v[236:237], 0, v[234:235]
	global_load_dwordx4 v[228:231], v[238:239], off
	global_load_dwordx4 v[228:231], v[238:239], off offset:1024
	s_waitcnt vmcnt(0)
	v_lshlrev_b32_e32 v0, 16, v4
	v_and_b32_e32 v1, 0xffff0000, v4
	v_lshlrev_b32_e32 v2, 16, v5
	v_and_b32_e32 v3, 0xffff0000, v5
	v_lshlrev_b32_e32 v4, 16, v6
	v_and_b32_e32 v5, 0xffff0000, v6
	v_lshlrev_b32_e32 v6, 16, v7
	v_and_b32_e32 v7, 0xffff0000, v7
	v_lshlrev_b32_e32 v16, 16, v8
	v_and_b32_e32 v17, 0xffff0000, v8
	v_lshlrev_b32_e32 v18, 16, v9
	v_and_b32_e32 v19, 0xffff0000, v9
	v_lshlrev_b32_e32 v8, 16, v10
	v_and_b32_e32 v9, 0xffff0000, v10
	v_lshlrev_b32_e32 v10, 16, v11
	v_and_b32_e32 v11, 0xffff0000, v11
	v_lshlrev_b32_e32 v168, 2, v48
	s_cbranch_execz .LBB0_512
